# post_tile V transposes: 32 ushort loads issued together instead of 4 serialized batches of 8
# speedup vs baseline: 1.0026x; 1.0013x over previous
.LBB0_544:
	v_mov_b32_e32 v4, v162
	v_ashrrev_i32_e32 v4, 5, v4
	v_and_b32_e32 v114, -8, v4
	v_add_u32_e32 v6, s12, v114
	v_mad_i64_i32 v[4:5], s[8:9], v6, s23, v[38:39]
	global_load_ushort v82, v[4:5], off
	v_or_b32_e32 v4, 1, v6
	v_mad_i64_i32 v[4:5], s[8:9], v4, s23, v[38:39]
	global_load_ushort v83, v[4:5], off
	v_or_b32_e32 v4, 2, v6
	v_mad_i64_i32 v[4:5], s[8:9], v4, s23, v[38:39]
	global_load_ushort v84, v[4:5], off
	v_or_b32_e32 v4, 3, v6
	v_mad_i64_i32 v[4:5], s[8:9], v4, s23, v[38:39]
	global_load_ushort v85, v[4:5], off
	v_or_b32_e32 v4, 4, v6
	v_mad_i64_i32 v[4:5], s[8:9], v4, s23, v[38:39]
	global_load_ushort v86, v[4:5], off
	v_or_b32_e32 v4, 5, v6
	v_mad_i64_i32 v[4:5], s[8:9], v4, s23, v[38:39]
	global_load_ushort v87, v[4:5], off
	v_or_b32_e32 v4, 6, v6
	v_mad_i64_i32 v[4:5], s[8:9], v4, s23, v[38:39]
	global_load_ushort v88, v[4:5], off
	v_or_b32_e32 v4, 7, v6
	v_mad_i64_i32 v[4:5], s[8:9], v4, s23, v[38:39]
	global_load_ushort v89, v[4:5], off
	v_add_u32_e32 v4, 0x200, v162
	v_ashrrev_i32_e32 v4, 5, v4
	v_and_b32_e32 v115, -8, v4
	v_add_u32_e32 v6, s12, v115
	v_mad_i64_i32 v[4:5], s[8:9], v6, s23, v[38:39]
	global_load_ushort v90, v[4:5], off
	v_or_b32_e32 v4, 1, v6
	v_mad_i64_i32 v[4:5], s[8:9], v4, s23, v[38:39]
	global_load_ushort v91, v[4:5], off
	v_or_b32_e32 v4, 2, v6
	v_mad_i64_i32 v[4:5], s[8:9], v4, s23, v[38:39]
	global_load_ushort v92, v[4:5], off
	v_or_b32_e32 v4, 3, v6
	v_mad_i64_i32 v[4:5], s[8:9], v4, s23, v[38:39]
	global_load_ushort v93, v[4:5], off
	v_or_b32_e32 v4, 4, v6
	v_mad_i64_i32 v[4:5], s[8:9], v4, s23, v[38:39]
	global_load_ushort v94, v[4:5], off
	v_or_b32_e32 v4, 5, v6
	v_mad_i64_i32 v[4:5], s[8:9], v4, s23, v[38:39]
	global_load_ushort v95, v[4:5], off
	v_or_b32_e32 v4, 6, v6
	v_mad_i64_i32 v[4:5], s[8:9], v4, s23, v[38:39]
	global_load_ushort v96, v[4:5], off
	v_or_b32_e32 v4, 7, v6
	v_mad_i64_i32 v[4:5], s[8:9], v4, s23, v[38:39]
	global_load_ushort v97, v[4:5], off
	v_add_u32_e32 v4, 0x400, v162
	v_ashrrev_i32_e32 v4, 5, v4
	v_and_b32_e32 v116, -8, v4
	v_add_u32_e32 v6, s12, v116
	v_mad_i64_i32 v[4:5], s[8:9], v6, s23, v[38:39]
	global_load_ushort v98, v[4:5], off
	v_or_b32_e32 v4, 1, v6
	v_mad_i64_i32 v[4:5], s[8:9], v4, s23, v[38:39]
	global_load_ushort v99, v[4:5], off
	v_or_b32_e32 v4, 2, v6
	v_mad_i64_i32 v[4:5], s[8:9], v4, s23, v[38:39]
	global_load_ushort v100, v[4:5], off
	v_or_b32_e32 v4, 3, v6
	v_mad_i64_i32 v[4:5], s[8:9], v4, s23, v[38:39]
	global_load_ushort v101, v[4:5], off
	v_or_b32_e32 v4, 4, v6
	v_mad_i64_i32 v[4:5], s[8:9], v4, s23, v[38:39]
	global_load_ushort v102, v[4:5], off
	v_or_b32_e32 v4, 5, v6
	v_mad_i64_i32 v[4:5], s[8:9], v4, s23, v[38:39]
	global_load_ushort v103, v[4:5], off
	v_or_b32_e32 v4, 6, v6
	v_mad_i64_i32 v[4:5], s[8:9], v4, s23, v[38:39]
	global_load_ushort v104, v[4:5], off
	v_or_b32_e32 v4, 7, v6
	v_mad_i64_i32 v[4:5], s[8:9], v4, s23, v[38:39]
	global_load_ushort v105, v[4:5], off
	v_add_u32_e32 v4, 0x600, v162
	v_ashrrev_i32_e32 v4, 5, v4
	v_and_b32_e32 v117, -8, v4
	v_add_u32_e32 v6, s12, v117
	v_mad_i64_i32 v[4:5], s[8:9], v6, s23, v[38:39]
	global_load_ushort v106, v[4:5], off
	v_or_b32_e32 v4, 1, v6
	v_mad_i64_i32 v[4:5], s[8:9], v4, s23, v[38:39]
	global_load_ushort v107, v[4:5], off
	v_or_b32_e32 v4, 2, v6
	v_mad_i64_i32 v[4:5], s[8:9], v4, s23, v[38:39]
	global_load_ushort v108, v[4:5], off
	v_or_b32_e32 v4, 3, v6
	v_mad_i64_i32 v[4:5], s[8:9], v4, s23, v[38:39]
	global_load_ushort v109, v[4:5], off
	v_or_b32_e32 v4, 4, v6
	v_mad_i64_i32 v[4:5], s[8:9], v4, s23, v[38:39]
	global_load_ushort v110, v[4:5], off
	v_or_b32_e32 v4, 5, v6
	v_mad_i64_i32 v[4:5], s[8:9], v4, s23, v[38:39]
	global_load_ushort v111, v[4:5], off
	v_or_b32_e32 v4, 6, v6
	v_mad_i64_i32 v[4:5], s[8:9], v4, s23, v[38:39]
	global_load_ushort v112, v[4:5], off
	v_or_b32_e32 v4, 7, v6
	v_mad_i64_i32 v[4:5], s[8:9], v4, s23, v[38:39]
	global_load_ushort v113, v[4:5], off
	s_waitcnt vmcnt(0)
	v_perm_b32 v5, v85, v84, s3
	v_perm_b32 v6, v87, v86, s3
	v_perm_b32 v7, v89, v88, s3
	v_perm_b32 v4, v83, v82, s3
	v_mov_b32_e32 v8, v114
	v_ashrrev_i32_e32 v9, 31, v8
	v_lshl_add_u64 v[8:9], v[8:9], 1, v[2:3]
	global_store_dwordx4 v[8:9], v[4:7], off
	s_nop 1
	v_perm_b32 v5, v93, v92, s3
	v_perm_b32 v6, v95, v94, s3
	v_perm_b32 v7, v97, v96, s3
	v_perm_b32 v4, v91, v90, s3
	v_mov_b32_e32 v8, v115
	v_ashrrev_i32_e32 v9, 31, v8
	v_lshl_add_u64 v[8:9], v[8:9], 1, v[2:3]
	global_store_dwordx4 v[8:9], v[4:7], off
	s_nop 1
	v_perm_b32 v5, v101, v100, s3
	v_perm_b32 v6, v103, v102, s3
	v_perm_b32 v7, v105, v104, s3
	v_perm_b32 v4, v99, v98, s3
	v_mov_b32_e32 v8, v116
	v_ashrrev_i32_e32 v9, 31, v8
	v_lshl_add_u64 v[8:9], v[8:9], 1, v[2:3]
	global_store_dwordx4 v[8:9], v[4:7], off
	s_nop 1
	v_perm_b32 v5, v109, v108, s3
	v_perm_b32 v6, v111, v110, s3
	v_perm_b32 v7, v113, v112, s3
	v_perm_b32 v4, v107, v106, s3
	v_mov_b32_e32 v8, v117
	v_ashrrev_i32_e32 v9, 31, v8
	v_lshl_add_u64 v[8:9], v[8:9], 1, v[2:3]
	global_store_dwordx4 v[8:9], v[4:7], off
	s_nop 1
	s_movk_i32 s0, 0x800
	global_load_dwordx2 v[2:3], v[44:45], off
	global_load_dwordx2 v[4:5], v[44:45], off offset:2048
	global_load_dwordx2 v[6:7], v[46:47], off
	v_mov_b32_e32 v10, v1
	v_mov_b32_e32 v11, v1
	v_cmp_gt_i32_e32 vcc, s2, v70
	v_lshlrev_b32_e32 v8, 1, v42
	v_mov_b64_e32 v[12:13], v[10:11]
	s_and_saveexec_b64 s[2:3], vcc
	s_cbranch_execz .LBB0_547
	v_add_u32_e32 v9, s12, v69
	v_add_u32_e32 v12, -1, v9
	v_mov_b64_e32 v[10:11], s[10:11]
	v_add_u32_e32 v9, -2, v9
	v_mad_i64_i32 v[12:13], s[8:9], v12, s23, v[10:11]
	v_mad_i64_i32 v[10:11], s[8:9], v9, s23, v[10:11]
	v_mov_b32_e32 v9, v1
	v_lshl_add_u64 v[12:13], v[12:13], 0, v[8:9]
	v_add_co_u32_e32 v14, vcc, 0x1000, v12
	v_lshl_add_u64 v[10:11], v[10:11], 0, v[8:9]
	s_nop 0
	v_addc_co_u32_e32 v15, vcc, 0, v13, vcc
	global_load_dword v14, v[14:15], off offset:560
	s_nop 0
	global_load_dword v15, v[12:13], off offset:2608
	v_add_co_u32_e32 v12, vcc, 0x1000, v10
	s_nop 1
	v_addc_co_u32_e32 v13, vcc, 0, v11, vcc
	global_load_dword v9, v[12:13], off offset:560
	global_load_dword v16, v[10:11], off offset:2608
	s_waitcnt vmcnt(3)
	v_lshlrev_b32_e32 v10, 16, v14
	s_waitcnt vmcnt(2)
	v_lshlrev_b32_e32 v12, 16, v15
	v_and_b32_e32 v13, 0xffff0000, v15
	v_and_b32_e32 v11, 0xffff0000, v14
	v_pk_mul_f32 v[10:11], v[10:11], v[12:13]
	s_waitcnt vmcnt(1)
	v_lshlrev_b32_e32 v12, 16, v9
	s_waitcnt vmcnt(0)
	v_lshlrev_b32_e32 v14, 16, v16
	v_and_b32_e32 v15, 0xffff0000, v16
	v_and_b32_e32 v13, 0xffff0000, v9
	v_pk_mul_f32 v[12:13], v[12:13], v[14:15]
